# attention stage DMA blocks: the s_nop behind each m0 write removed by putting the next address add between the m0 write and the DMA (17 sites)
# speedup vs baseline: 1.0010x; 1.0010x over previous
; #define LAS __attribute__((address_space(3)))
; #define ATT_STAGE(t_, buf_) do { const char* gb_ = gbase + (size_t)(t_) * tstep; _Pragma("unroll") for (int j_ = 0; j_ < NPW * REP_DMA; ++j_) \
;         __builtin_amdgcn_global_load_lds((const unsigned*)(gb_ + ATT_CJ(j_ % NPW) + vbase), (LAS unsigned*)(lds + (buf_) * STAGE + (wid * NPW + j_ % NPW) * 1024), 16, 0, 0); } while (0)
; template <int DV, int NMAP> ...
;     ...
;     const int loff = (fr * 64 + fq * 16) ^ (((fr >> 3) & 1) << 5);
;     f32x4 o[DV / 16][2];
; #pragma unroll
;     for (int db = 0; db < DV / 16; ++db) { o[db][0] = (f32x4){0.f, 0.f, 0.f, 0.f}; o[db][1] = (f32x4){0.f, 0.f, 0.f, 0.f}; }
;     float lsum[2] = {0.f, 0.f};
;     const LAS float* tab = (const LAS float*)(lds + TAB_OFF);
;     asm volatile("s_waitcnt vmcnt(0)" ::: "memory");
;     ATT_STAGE(T0, 0);
;     if ((wid >> 2) ^ (wid & 1)) __builtin_amdgcn_s_setprio(2);
.LBB0_315:
	s_add_u32 s70, s88, s44
	s_addc_u32 s71, s89, s45
	s_lshl_b32 s34, s34, 13
	s_add_i32 s34, s34, 0
	v_lshl_add_u64 v[4:5], s[70:71], 0, v[204:205]
	s_mov_b32 m0, s34
	v_lshl_add_u64 v[6:7], v[4:5], 0, 64
	global_load_lds_dwordx4 v204, s[70:71]
	s_add_i32 m0, s34, 0x400
	v_mov_b64_e32 v[214:215], 0x400
	global_load_lds_dwordx4 v[6:7], off
	s_add_i32 m0, s34, 0x800
	v_lshl_add_u64 v[6:7], v[4:5], 0, s[72:73]
	global_load_lds_dwordx4 v[6:7], off
	s_add_i32 m0, s34, 0xc00
	v_lshl_add_u64 v[6:7], v[4:5], 0, s[68:69]
	global_load_lds_dwordx4 v[6:7], off
	s_add_i32 m0, s34, 0x1000
	v_lshl_add_u64 v[6:7], v[4:5], 0, s[38:39]
	global_load_lds_dwordx4 v[6:7], off
	s_add_i32 m0, s34, 0x1400
	v_lshl_add_u64 v[6:7], v[4:5], 0, s[16:17]
	global_load_lds_dwordx4 v[6:7], off
	v_lshl_add_u64 v[6:7], v[4:5], 0, s[10:11]
	s_add_i32 m0, s34, 0x1800
	v_lshl_add_u64 v[4:5], v[4:5], 0, s[8:9]
	global_load_lds_dwordx4 v[6:7], off
	s_add_i32 m0, s34, 0x1c00
	s_bfe_u32 s8, s20, 0x10006
	global_load_lds_dwordx4 v[4:5], off
	s_cmp_eq_u32 s21, s8
	s_cbranch_scc1 .LBB0_317
	s_setprio 2

; #define ATT_STAGE(t_, buf_) do { const char* gb_ = gbase + (size_t)(t_) * tstep; _Pragma("unroll") for (int j_ = 0; j_ < NPW * REP_DMA; ++j_) \
;         __builtin_amdgcn_global_load_lds((const unsigned*)(gb_ + ATT_CJ(j_ % NPW) + vbase), (LAS unsigned*)(lds + (buf_) * STAGE + (wid * NPW + j_ % NPW) * 1024), 16, 0, 0); } while (0)
; template <int DV, int NMAP> ...
;     ...
;     for (int t = T0; t <= T1; ++t) {
;         const int cur = (t - T0) & 1;
;         asm volatile("s_waitcnt vmcnt(0)" ::: "memory");
;         asm volatile("s_waitcnt lgkmcnt(0)" ::: "memory"); __builtin_amdgcn_s_barrier(); asm volatile("" ::: "memory");
;         const bool inr = (t >= lo_w && t <= cw);
;         if (t < T1 && (isk || !inr)) ATT_STAGE(t + 1, cur ^ 1);
.LBB0_320:
	s_and_b32 s52, s84, 1
	s_cmp_le_u32 s84, s37
	s_cselect_b64 s[44:45], -1, 0
	s_cmp_gt_u32 s84, s37
	s_waitcnt vmcnt(0)
	s_cselect_b64 s[70:71], -1, 0
	s_cmp_le_u32 s84, s35
	s_waitcnt lgkmcnt(0)
	s_barrier
	s_cselect_b64 s[78:79], -1, 0
	s_or_b64 s[70:71], s[4:5], s[70:71]
	s_and_b64 s[70:71], s[78:79], s[70:71]
	s_andn2_b64 vcc, exec, s[70:71]
	s_cbranch_vccnz .LBB0_322
	s_lshl_b32 s53, s52, 16
	s_xor_b32 s53, s53, 0x10000
	s_add_i32 s53, s34, s53
	s_mov_b32 m0, s53
	v_lshl_add_u64 v[160:161], v[220:221], 0, 64
	global_load_lds_dwordx4 v[220:221], off
	s_add_i32 m0, s53, 0x400
	s_nop 0
	global_load_lds_dwordx4 v[160:161], off
	s_add_i32 m0, s53, 0x800
	v_lshl_add_u64 v[160:161], v[220:221], 0, s[8:9]
	global_load_lds_dwordx4 v[160:161], off
	s_add_i32 m0, s53, 0xc00
	v_lshl_add_u64 v[160:161], v[220:221], 0, s[10:11]
	global_load_lds_dwordx4 v[160:161], off
	s_add_i32 m0, s53, 0x1000
	v_lshl_add_u64 v[160:161], v[220:221], 0, s[16:17]
	global_load_lds_dwordx4 v[160:161], off
	s_add_i32 m0, s53, 0x1400
	v_lshl_add_u64 v[160:161], v[220:221], 0, s[38:39]
	global_load_lds_dwordx4 v[160:161], off
	s_add_i32 m0, s53, 0x1800
	v_lshl_add_u64 v[160:161], v[220:221], 0, s[72:73]
	global_load_lds_dwordx4 v[160:161], off
	s_add_i32 m0, s53, 0x1c00
	v_lshl_add_u64 v[160:161], v[220:221], 0, s[76:77]
	global_load_lds_dwordx4 v[160:161], off

; template <int N> __device__ __forceinline__ void lgkm_pin(bf16x8& f) { (void)f; asm volatile("s_waitcnt lgkmcnt(%0)" :: "n"(N) : "memory"); }
; #define ATT_STAGE(t_, buf_) do { const char* gb_ = gbase + (size_t)(t_) * tstep; _Pragma("unroll") for (int j_ = 0; j_ < NPW * REP_DMA; ++j_) \
;         __builtin_amdgcn_global_load_lds((const unsigned*)(gb_ + ATT_CJ(j_ % NPW) + vbase), (LAS unsigned*)(lds + (buf_) * STAGE + (wid * NPW + j_ % NPW) * 1024), 16, 0, 0); } while (0)
; #define ATT_KLD(i_) lds_rd(stk, (((i_) >> 2) >> 1) * 8192 + (((i_) & 3) * 2 + (((i_) >> 2) & 1)) * 1024)
; template <int DV, int NMAP> ...
;     ...
;             { bf16x8 f0 = ATT_KLD(0), f1 = ATT_KLD(1), f2 = ATT_KLD(2);
; #pragma unroll
;               for (int i = 0; i < 16; ++i) {
;                   bf16x8 cur = f0; f0 = f1; f1 = f2; if (i + 3 < 16) f2 = ATT_KLD(i + 3);
;                   if (i + 3 < 16) lgkm_pin<3>(cur); else if (i + 2 < 16) lgkm_pin<2>(cur); else if (i + 1 < 16) lgkm_pin<1>(cur); else lgkm_pin<0>(cur);
;                   __builtin_amdgcn_sched_barrier(0);
;                   s[i & 3][0] = __builtin_amdgcn_mfma_f32_16x16x32_bf16(cur, q[0][i >> 2], s[i & 3][0], 0, 0, 0);
;                   s[i & 3][1] = __builtin_amdgcn_mfma_f32_16x16x32_bf16(cur, q[1][i >> 2], s[i & 3][1], 0, 0, 0);
;                   __builtin_amdgcn_sched_barrier(0);
;               } }
;             if (t < T1 && !isk) ATT_STAGE(t + 1, cur ^ 1);
.Lbt_qk:
	s_waitcnt lgkmcnt(3)
	s_nop 0
	v_mfma_f32_16x16x32_bf16 v[176:179], v[160:163], v[124:127], 0
	v_mfma_f32_16x16x32_bf16 v[160:163], v[160:163], v[140:143], 0
	ds_read_b128 v[180:183], v204 offset:0x400
	s_waitcnt lgkmcnt(3)
	v_mfma_f32_16x16x32_bf16 v[184:187], v[164:167], v[124:127], 0
	v_mfma_f32_16x16x32_bf16 v[164:167], v[164:167], v[140:143], 0
	ds_read_b128 v[188:191], v204 offset:0xc00
	s_waitcnt lgkmcnt(3)
	v_mfma_f32_16x16x32_bf16 v[192:195], v[168:171], v[124:127], 0
	v_mfma_f32_16x16x32_bf16 v[168:171], v[168:171], v[140:143], 0
	ds_read_b128 v[196:199], v204 offset:0x1400
	s_waitcnt lgkmcnt(3)
	v_mfma_f32_16x16x32_bf16 v[200:203], v[172:175], v[124:127], 0
	v_mfma_f32_16x16x32_bf16 v[172:175], v[172:175], v[140:143], 0
	ds_read_b128 v[240:243], v204 offset:0x1c00
	s_waitcnt lgkmcnt(3)
	v_mfma_f32_16x16x32_bf16 v[176:179], v[180:183], v[128:131], v[176:179]
	v_mfma_f32_16x16x32_bf16 v[160:163], v[180:183], v[144:147], v[160:163]
	ds_read_b128 v[180:183], v204 offset:0x2000
	s_waitcnt lgkmcnt(3)
	v_mfma_f32_16x16x32_bf16 v[164:167], v[188:191], v[144:147], v[164:167]
	v_mfma_f32_16x16x32_bf16 v[184:187], v[188:191], v[128:131], v[184:187]
	ds_read_b128 v[188:191], v204 offset:0x2800
	s_waitcnt lgkmcnt(3)
	v_mfma_f32_16x16x32_bf16 v[168:171], v[196:199], v[144:147], v[168:171]
	v_mfma_f32_16x16x32_bf16 v[192:195], v[196:199], v[128:131], v[192:195]
	ds_read_b128 v[196:199], v204 offset:0x3000
	s_waitcnt lgkmcnt(3)
	v_mfma_f32_16x16x32_bf16 v[172:175], v[240:243], v[144:147], v[172:175]
	v_mfma_f32_16x16x32_bf16 v[200:203], v[240:243], v[128:131], v[200:203]
	ds_read_b128 v[240:243], v204 offset:0x3800
	s_waitcnt lgkmcnt(3)
	v_mfma_f32_16x16x32_bf16 v[176:179], v[180:183], v[132:135], v[176:179]
	v_mfma_f32_16x16x32_bf16 v[160:163], v[180:183], v[148:151], v[160:163]
	ds_read_b128 v[180:183], v204 offset:0x2400
	s_waitcnt lgkmcnt(3)
	v_mfma_f32_16x16x32_bf16 v[164:167], v[188:191], v[148:151], v[164:167]
	v_mfma_f32_16x16x32_bf16 v[184:187], v[188:191], v[132:135], v[184:187]
	ds_read_b128 v[244:247], v204 offset:0x2c00
	s_waitcnt lgkmcnt(3)
	v_mfma_f32_16x16x32_bf16 v[168:171], v[196:199], v[148:151], v[168:171]
	v_mfma_f32_16x16x32_bf16 v[192:195], v[196:199], v[132:135], v[192:195]
	ds_read_b128 v[248:251], v204 offset:0x3400
	s_waitcnt lgkmcnt(3)
	v_mfma_f32_16x16x32_bf16 v[200:203], v[240:243], v[132:135], v[200:203]
	v_mfma_f32_16x16x32_bf16 v[240:243], v[240:243], v[148:151], v[172:175]
	ds_read_b128 v[206:209], v204 offset:0x3c00
	s_waitcnt lgkmcnt(3)
	v_mfma_f32_16x16x32_bf16 v[196:199], v[180:183], v[136:139], v[176:179]
	v_mfma_f32_16x16x32_bf16 v[180:183], v[180:183], v[152:155], v[160:163]
	s_waitcnt lgkmcnt(2)
	v_mfma_f32_16x16x32_bf16 v[188:191], v[244:247], v[136:139], v[184:187]
	v_mfma_f32_16x16x32_bf16 v[176:179], v[244:247], v[152:155], v[164:167]
	s_waitcnt lgkmcnt(1)
	v_mfma_f32_16x16x32_bf16 v[172:175], v[248:251], v[136:139], v[192:195]
	v_mfma_f32_16x16x32_bf16 v[168:171], v[248:251], v[152:155], v[168:171]
	s_waitcnt lgkmcnt(0)
	v_mfma_f32_16x16x32_bf16 v[164:167], v[206:209], v[136:139], v[200:203]
	v_mfma_f32_16x16x32_bf16 v[160:163], v[206:209], v[152:155], v[240:243]
	s_cmp_gt_u32 s84, s35
	s_cselect_b64 s[52:53], -1, 0
	s_or_b64 s[52:53], s[4:5], s[52:53]
	s_and_b64 vcc, exec, s[52:53]
	s_cbranch_vccnz .LBB0_325
	s_xor_b32 s45, s45, 0x10000
	s_add_i32 s45, s34, s45
	s_mov_b32 m0, s45
	v_lshl_add_u64 v[184:185], v[220:221], 0, 64
	global_load_lds_dwordx4 v[220:221], off
	s_add_i32 m0, s45, 0x400
	s_mov_b64 s[52:53], 0x100040
	global_load_lds_dwordx4 v[184:185], off
	s_add_i32 m0, s45, 0x800
	v_lshl_add_u64 v[184:185], v[220:221], 0, s[24:25]
	global_load_lds_dwordx4 v[184:185], off
	s_add_i32 m0, s45, 0xc00
	v_lshl_add_u64 v[184:185], v[220:221], 0, s[12:13]
	global_load_lds_dwordx4 v[184:185], off
	s_add_i32 m0, s45, 0x1000
	v_lshl_add_u64 v[184:185], v[220:221], 0, s[30:31]
	global_load_lds_dwordx4 v[184:185], off
	v_lshl_add_u64 v[184:185], v[220:221], 0, s[52:53]
	s_add_i32 m0, s45, 0x1400
	s_mov_b64 s[52:53], 0x180000
	global_load_lds_dwordx4 v[184:185], off
	v_lshl_add_u64 v[184:185], v[220:221], 0, s[52:53]
	s_add_i32 m0, s45, 0x1800
	s_mov_b64 s[52:53], 0x180040
	global_load_lds_dwordx4 v[184:185], off
	s_add_i32 m0, s45, 0x1c00
	v_lshl_add_u64 v[184:185], v[220:221], 0, s[52:53]
	global_load_lds_dwordx4 v[184:185], off

; #define ATT_STAGE(t_, buf_) do { const char* gb_ = gbase + (size_t)(t_) * tstep; _Pragma("unroll") for (int j_ = 0; j_ < NPW * REP_DMA; ++j_) \
;         __builtin_amdgcn_global_load_lds((const unsigned*)(gb_ + ATT_CJ(j_ % NPW) + vbase), (LAS unsigned*)(lds + (buf_) * STAGE + (wid * NPW + j_ % NPW) * 1024), 16, 0, 0); } while (0)
; template <int DV, int NMAP> ...
;     ...
;     for (int t = T0; t <= T1; ++t) {
;         const int cur = (t - T0) & 1;
;         asm volatile("s_waitcnt vmcnt(0)" ::: "memory");
;         asm volatile("s_waitcnt lgkmcnt(0)" ::: "memory"); __builtin_amdgcn_s_barrier(); asm volatile("" ::: "memory");
;         const bool inr = (t >= lo_w && t <= cw);
;         if (t < T1 && (isk || !inr)) ATT_STAGE(t + 1, cur ^ 1);
.LBB0_351:
	s_add_i32 s57, s57, 1
	s_and_b32 s52, s57, 1
	s_cmp_lt_u32 s57, s36
	s_cselect_b64 s[44:45], -1, 0
	s_cmp_gt_i32 s57, s35
	s_cselect_b64 s[68:69], -1, 0
	s_or_b64 s[44:45], s[44:45], s[68:69]
	s_cmp_ge_i32 s57, s34
	s_waitcnt vmcnt(0)
	s_cselect_b64 s[72:73], -1, 0
	s_cmp_lt_i32 s57, s34
	s_waitcnt lgkmcnt(0)
	s_barrier
	s_cselect_b64 s[68:69], -1, 0
	s_or_b64 s[70:71], s[6:7], s[44:45]
	s_and_b64 s[68:69], s[68:69], s[70:71]
	s_andn2_b64 vcc, exec, s[68:69]
	s_cbranch_vccnz .LBB0_353
	s_lshl_b32 s53, s52, 15
	s_xor_b32 s53, s53, 0x8000
	s_add_i32 s53, s23, s53
	v_lshl_add_u64 v[96:97], s[38:39], 0, v[204:205]
	s_mov_b32 m0, s53
	s_nop 0
	global_load_lds_dwordx4 v[96:97], off
	s_add_i32 m0, s53, 0x400
	v_lshl_add_u64 v[96:97], v[96:97], 0, 64
	global_load_lds_dwordx4 v[96:97], off
	s_add_i32 m0, s53, 0x800
	v_lshl_add_u64 v[96:97], s[16:17], 0, v[204:205]
	global_load_lds_dwordx4 v[96:97], off
	s_add_i32 m0, s53, 0xc00
	v_lshl_add_u64 v[96:97], s[10:11], 0, v[204:205]
	global_load_lds_dwordx4 v[96:97], off
